# loop heads (attention loop + 8 GEMM K-loops) aligned to 64 bytes with p2align (on top of v15)
# baseline (speedup 1.0000x reference)
.LBB0_283:
	s_ashr_i32 s25, s24, 31
	s_lshl_b64 s[26:27], s[24:25], 19
	s_add_u32 s26, s19, s26
	s_addc_u32 s27, s21, s27
	s_and_b64 s[28:29], s[0:1], exec
	s_cselect_b32 s25, s27, s31
	s_cselect_b32 s73, s26, s30
	s_ashr_i32 s23, s22, 31
	s_lshl_b64 s[28:29], s[22:23], 19
	s_add_u32 s28, s38, s28
	s_addc_u32 s29, s39, s29
	s_and_b64 s[34:35], s[0:1], exec
	s_cselect_b32 s23, s29, s5
	s_cselect_b32 s74, s28, s4
	s_add_u32 s75, s4, 0x100
	s_addc_u32 s81, s5, 0
	s_add_u32 s4, s30, 0x40080
	s_addc_u32 s5, s31, 0
	s_mov_b32 s82, -2
	v_mov_b64_e32 v[0:1], 0
	v_mov_b64_e32 v[2:3], 0
	v_mov_b64_e32 v[4:5], 0
	v_mov_b64_e32 v[6:7], 0
	v_mov_b64_e32 v[8:9], 0
	v_mov_b64_e32 v[10:11], 0
	v_mov_b64_e32 v[12:13], 0
	v_mov_b64_e32 v[14:15], 0
	v_mov_b64_e32 v[16:17], 0
	v_mov_b64_e32 v[18:19], 0
	v_mov_b64_e32 v[20:21], 0
	v_mov_b64_e32 v[22:23], 0
	v_mov_b64_e32 v[24:25], 0
	v_mov_b64_e32 v[26:27], 0
	v_mov_b64_e32 v[28:29], 0
	v_mov_b64_e32 v[30:31], 0
	v_mov_b64_e32 v[32:33], 0
	v_mov_b64_e32 v[34:35], 0
	v_mov_b64_e32 v[36:37], 0
	v_mov_b64_e32 v[38:39], 0
	v_mov_b64_e32 v[40:41], 0
	v_mov_b64_e32 v[42:43], 0
	v_mov_b64_e32 v[44:45], 0
	v_mov_b64_e32 v[46:47], 0
	v_mov_b64_e32 v[48:49], 0
	v_mov_b64_e32 v[50:51], 0
	v_mov_b64_e32 v[52:53], 0
	v_mov_b64_e32 v[54:55], 0
	v_mov_b64_e32 v[56:57], 0
	v_mov_b64_e32 v[58:59], 0
	v_mov_b64_e32 v[60:61], 0
	v_mov_b64_e32 v[62:63], 0
	v_mov_b64_e32 v[64:65], 0
	v_mov_b64_e32 v[66:67], 0
	v_mov_b64_e32 v[68:69], 0
	v_mov_b64_e32 v[70:71], 0
	v_mov_b64_e32 v[72:73], 0
	v_mov_b64_e32 v[74:75], 0
	v_mov_b64_e32 v[76:77], 0
	v_mov_b64_e32 v[78:79], 0
	v_mov_b64_e32 v[80:81], 0
	v_mov_b64_e32 v[82:83], 0
	v_mov_b64_e32 v[84:85], 0
	v_mov_b64_e32 v[86:87], 0
	v_mov_b64_e32 v[88:89], 0
	v_mov_b64_e32 v[90:91], 0
	v_mov_b64_e32 v[92:93], 0
	v_mov_b64_e32 v[94:95], 0
	v_mov_b64_e32 v[96:97], 0
	v_mov_b64_e32 v[98:99], 0
	v_mov_b64_e32 v[100:101], 0
	v_mov_b64_e32 v[102:103], 0
	v_mov_b64_e32 v[104:105], 0
	v_mov_b64_e32 v[106:107], 0
	v_mov_b64_e32 v[108:109], 0
	v_mov_b64_e32 v[110:111], 0
	v_mov_b64_e32 v[112:113], 0
	v_mov_b64_e32 v[114:115], 0
	v_mov_b64_e32 v[116:117], 0
	v_mov_b64_e32 v[118:119], 0
	v_mov_b64_e32 v[120:121], 0
	v_mov_b64_e32 v[122:123], 0
	v_mov_b64_e32 v[124:125], 0
	v_mov_b64_e32 v[126:127], 0
	.p2align 6

.LBB0_357:
	s_add_u32 s67, s20, 0x100
	v_mov_b32_e32 v0, 0
	s_addc_u32 s72, s21, 0
	s_mov_b32 s73, -2
	s_waitcnt lgkmcnt(0)
	v_mov_b32_e32 v1, v0
	v_mov_b32_e32 v2, v0
	v_mov_b32_e32 v3, v0
	v_mov_b32_e32 v4, v0
	v_mov_b32_e32 v5, v0
	v_mov_b32_e32 v6, v0
	v_mov_b32_e32 v7, v0
	v_mov_b32_e32 v8, v0
	v_mov_b32_e32 v9, v0
	v_mov_b32_e32 v10, v0
	v_mov_b32_e32 v11, v0
	v_mov_b32_e32 v12, v0
	v_mov_b32_e32 v13, v0
	v_mov_b32_e32 v14, v0
	v_mov_b32_e32 v15, v0
	v_mov_b32_e32 v16, v0
	v_mov_b32_e32 v17, v0
	v_mov_b32_e32 v18, v0
	v_mov_b32_e32 v19, v0
	v_mov_b32_e32 v20, v0
	v_mov_b32_e32 v21, v0
	v_mov_b32_e32 v22, v0
	v_mov_b32_e32 v23, v0
	v_mov_b32_e32 v24, v0
	v_mov_b32_e32 v25, v0
	v_mov_b32_e32 v26, v0
	v_mov_b32_e32 v27, v0
	v_mov_b32_e32 v28, v0
	v_mov_b32_e32 v29, v0
	v_mov_b32_e32 v30, v0
	v_mov_b32_e32 v31, v0
	v_mov_b32_e32 v64, v0
	v_mov_b32_e32 v65, v0
	v_mov_b32_e32 v66, v0
	v_mov_b32_e32 v67, v0
	v_mov_b32_e32 v68, v0
	v_mov_b32_e32 v69, v0
	v_mov_b32_e32 v70, v0
	v_mov_b32_e32 v71, v0
	v_mov_b32_e32 v72, v0
	v_mov_b32_e32 v73, v0
	v_mov_b32_e32 v74, v0
	v_mov_b32_e32 v75, v0
	v_mov_b32_e32 v76, v0
	v_mov_b32_e32 v77, v0
	v_mov_b32_e32 v78, v0
	v_mov_b32_e32 v79, v0
	v_mov_b32_e32 v80, v0
	v_mov_b32_e32 v81, v0
	v_mov_b32_e32 v82, v0
	v_mov_b32_e32 v83, v0
	v_mov_b32_e32 v84, v0
	v_mov_b32_e32 v85, v0
	v_mov_b32_e32 v86, v0
	v_mov_b32_e32 v87, v0
	v_mov_b32_e32 v88, v0
	v_mov_b32_e32 v89, v0
	v_mov_b32_e32 v90, v0
	v_mov_b32_e32 v91, v0
	v_mov_b32_e32 v92, v0
	v_mov_b32_e32 v93, v0
	v_mov_b32_e32 v94, v0
	v_mov_b32_e32 v95, v0
	v_mov_b32_e32 v32, v0
	v_mov_b32_e32 v33, v0
	v_mov_b32_e32 v34, v0
	v_mov_b32_e32 v35, v0
	v_mov_b32_e32 v36, v0
	v_mov_b32_e32 v37, v0
	v_mov_b32_e32 v38, v0
	v_mov_b32_e32 v39, v0
	v_mov_b32_e32 v40, v0
	v_mov_b32_e32 v41, v0
	v_mov_b32_e32 v42, v0
	v_mov_b32_e32 v43, v0
	v_mov_b32_e32 v44, v0
	v_mov_b32_e32 v45, v0
	v_mov_b32_e32 v46, v0
	v_mov_b32_e32 v47, v0
	v_mov_b32_e32 v48, v0
	v_mov_b32_e32 v49, v0
	v_mov_b32_e32 v50, v0
	v_mov_b32_e32 v51, v0
	v_mov_b32_e32 v52, v0
	v_mov_b32_e32 v53, v0
	v_mov_b32_e32 v54, v0
	v_mov_b32_e32 v55, v0
	v_mov_b32_e32 v56, v0
	v_mov_b32_e32 v57, v0
	v_mov_b32_e32 v58, v0
	v_mov_b32_e32 v59, v0
	v_mov_b32_e32 v60, v0
	v_mov_b32_e32 v61, v0
	v_mov_b32_e32 v62, v0
	v_mov_b32_e32 v63, v0
	v_mov_b32_e32 v104, v0
	v_mov_b32_e32 v105, v0
	v_mov_b32_e32 v106, v0
	v_mov_b32_e32 v107, v0
	v_mov_b32_e32 v108, v0
	v_mov_b32_e32 v109, v0
	v_mov_b32_e32 v110, v0
	v_mov_b32_e32 v111, v0
	v_mov_b32_e32 v112, v0
	v_mov_b32_e32 v113, v0
	v_mov_b32_e32 v114, v0
	v_mov_b32_e32 v115, v0
	v_mov_b32_e32 v116, v0
	v_mov_b32_e32 v117, v0
	v_mov_b32_e32 v118, v0
	v_mov_b32_e32 v119, v0
	v_mov_b32_e32 v120, v0
	v_mov_b32_e32 v121, v0
	v_mov_b32_e32 v122, v0
	v_mov_b32_e32 v123, v0
	v_mov_b32_e32 v124, v0
	v_mov_b32_e32 v125, v0
	v_mov_b32_e32 v126, v0
	v_mov_b32_e32 v127, v0
	v_mov_b32_e32 v128, v0
	v_mov_b32_e32 v129, v0
	v_mov_b32_e32 v130, v0
	v_mov_b32_e32 v131, v0
	v_mov_b32_e32 v132, v0
	v_mov_b32_e32 v133, v0
	v_mov_b32_e32 v134, v0
	v_mov_b32_e32 v135, v0
	.p2align 6

.LBB0_441:
	s_ashr_i32 s21, s20, 31
	s_lshl_b64 s[22:23], s[20:21], 19
	s_add_u32 s22, s17, s22
	s_addc_u32 s23, s38, s23
	s_and_b64 s[24:25], s[2:3], exec
	s_cselect_b32 s21, s23, s31
	s_cselect_b32 s64, s22, s30
	s_ashr_i32 s19, s18, 31
	s_lshl_b64 s[24:25], s[18:19], 19
	s_add_u32 s24, s39, s24
	s_addc_u32 s25, s40, s25
	s_and_b64 s[34:35], s[2:3], exec
	s_cselect_b32 s19, s25, s29
	s_cselect_b32 s65, s24, s28
	s_add_u32 s66, s28, 0x100
	s_addc_u32 s67, s29, 0
	s_add_u32 s28, s30, 0x40080
	s_addc_u32 s29, s31, 0
	s_mov_b32 s72, -2
	v_mov_b64_e32 v[0:1], 0
	v_mov_b64_e32 v[2:3], 0
	v_mov_b64_e32 v[4:5], 0
	v_mov_b64_e32 v[6:7], 0
	v_mov_b64_e32 v[8:9], 0
	v_mov_b64_e32 v[10:11], 0
	v_mov_b64_e32 v[12:13], 0
	v_mov_b64_e32 v[14:15], 0
	v_mov_b64_e32 v[16:17], 0
	v_mov_b64_e32 v[18:19], 0
	v_mov_b64_e32 v[20:21], 0
	v_mov_b64_e32 v[22:23], 0
	v_mov_b64_e32 v[24:25], 0
	v_mov_b64_e32 v[26:27], 0
	v_mov_b64_e32 v[28:29], 0
	v_mov_b64_e32 v[30:31], 0
	v_mov_b64_e32 v[32:33], 0
	v_mov_b64_e32 v[34:35], 0
	v_mov_b64_e32 v[36:37], 0
	v_mov_b64_e32 v[38:39], 0
	v_mov_b64_e32 v[40:41], 0
	v_mov_b64_e32 v[42:43], 0
	v_mov_b64_e32 v[44:45], 0
	v_mov_b64_e32 v[46:47], 0
	v_mov_b64_e32 v[48:49], 0
	v_mov_b64_e32 v[50:51], 0
	v_mov_b64_e32 v[52:53], 0
	v_mov_b64_e32 v[54:55], 0
	v_mov_b64_e32 v[56:57], 0
	v_mov_b64_e32 v[58:59], 0
	v_mov_b64_e32 v[60:61], 0
	v_mov_b64_e32 v[62:63], 0
	v_mov_b64_e32 v[64:65], 0
	v_mov_b64_e32 v[66:67], 0
	v_mov_b64_e32 v[68:69], 0
	v_mov_b64_e32 v[70:71], 0
	v_mov_b64_e32 v[72:73], 0
	v_mov_b64_e32 v[74:75], 0
	v_mov_b64_e32 v[76:77], 0
	v_mov_b64_e32 v[78:79], 0
	v_mov_b64_e32 v[80:81], 0
	v_mov_b64_e32 v[82:83], 0
	v_mov_b64_e32 v[84:85], 0
	v_mov_b64_e32 v[86:87], 0
	v_mov_b64_e32 v[88:89], 0
	v_mov_b64_e32 v[90:91], 0
	v_mov_b64_e32 v[92:93], 0
	v_mov_b64_e32 v[94:95], 0
	v_mov_b64_e32 v[96:97], 0
	v_mov_b64_e32 v[98:99], 0
	v_mov_b64_e32 v[100:101], 0
	v_mov_b64_e32 v[102:103], 0
	v_mov_b64_e32 v[104:105], 0
	v_mov_b64_e32 v[106:107], 0
	v_mov_b64_e32 v[108:109], 0
	v_mov_b64_e32 v[110:111], 0
	v_mov_b64_e32 v[112:113], 0
	v_mov_b64_e32 v[114:115], 0
	v_mov_b64_e32 v[116:117], 0
	v_mov_b64_e32 v[118:119], 0
	v_mov_b64_e32 v[120:121], 0
	v_mov_b64_e32 v[122:123], 0
	v_mov_b64_e32 v[124:125], 0
	v_mov_b64_e32 v[126:127], 0
	.p2align 6

.Latt_prio_done:
	.p2align 6

.LBB0_759:
	s_ashr_i32 s17, s16, 31
	s_lshl_b64 s[18:19], s[16:17], 18
	s_add_u32 s18, s31, s18
	s_addc_u32 s19, s34, s19
	s_and_b64 s[20:21], s[2:3], exec
	s_cselect_b32 s17, s19, s27
	s_cselect_b32 s52, s18, s26
	s_ashr_i32 s15, s14, 31
	s_lshl_b64 s[20:21], s[14:15], 18
	s_add_u32 s20, s35, s20
	s_addc_u32 s21, s38, s21
	s_and_b64 s[28:29], s[2:3], exec
	s_cselect_b32 s15, s21, s25
	s_cselect_b32 s53, s20, s24
	s_add_u32 s54, s24, 0x100
	s_addc_u32 s55, s25, 0
	s_add_u32 s24, s26, 0x20080
	s_addc_u32 s25, s27, 0
	s_mov_b32 s56, -2
	v_mov_b64_e32 v[0:1], 0
	v_mov_b64_e32 v[2:3], 0
	v_mov_b64_e32 v[4:5], 0
	v_mov_b64_e32 v[6:7], 0
	v_mov_b64_e32 v[8:9], 0
	v_mov_b64_e32 v[10:11], 0
	v_mov_b64_e32 v[12:13], 0
	v_mov_b64_e32 v[14:15], 0
	v_mov_b64_e32 v[16:17], 0
	v_mov_b64_e32 v[18:19], 0
	v_mov_b64_e32 v[20:21], 0
	v_mov_b64_e32 v[22:23], 0
	v_mov_b64_e32 v[24:25], 0
	v_mov_b64_e32 v[26:27], 0
	v_mov_b64_e32 v[28:29], 0
	v_mov_b64_e32 v[30:31], 0
	v_mov_b64_e32 v[32:33], 0
	v_mov_b64_e32 v[34:35], 0
	v_mov_b64_e32 v[36:37], 0
	v_mov_b64_e32 v[38:39], 0
	v_mov_b64_e32 v[40:41], 0
	v_mov_b64_e32 v[42:43], 0
	v_mov_b64_e32 v[44:45], 0
	v_mov_b64_e32 v[46:47], 0
	v_mov_b64_e32 v[48:49], 0
	v_mov_b64_e32 v[50:51], 0
	v_mov_b64_e32 v[52:53], 0
	v_mov_b64_e32 v[54:55], 0
	v_mov_b64_e32 v[56:57], 0
	v_mov_b64_e32 v[58:59], 0
	v_mov_b64_e32 v[60:61], 0
	v_mov_b64_e32 v[62:63], 0
	v_mov_b64_e32 v[64:65], 0
	v_mov_b64_e32 v[66:67], 0
	v_mov_b64_e32 v[68:69], 0
	v_mov_b64_e32 v[70:71], 0
	v_mov_b64_e32 v[72:73], 0
	v_mov_b64_e32 v[74:75], 0
	v_mov_b64_e32 v[76:77], 0
	v_mov_b64_e32 v[78:79], 0
	v_mov_b64_e32 v[80:81], 0
	v_mov_b64_e32 v[82:83], 0
	v_mov_b64_e32 v[84:85], 0
	v_mov_b64_e32 v[86:87], 0
	v_mov_b64_e32 v[88:89], 0
	v_mov_b64_e32 v[90:91], 0
	v_mov_b64_e32 v[92:93], 0
	v_mov_b64_e32 v[94:95], 0
	v_mov_b64_e32 v[96:97], 0
	v_mov_b64_e32 v[98:99], 0
	v_mov_b64_e32 v[100:101], 0
	v_mov_b64_e32 v[102:103], 0
	v_mov_b64_e32 v[104:105], 0
	v_mov_b64_e32 v[106:107], 0
	v_mov_b64_e32 v[108:109], 0
	v_mov_b64_e32 v[110:111], 0
	v_mov_b64_e32 v[112:113], 0
	v_mov_b64_e32 v[114:115], 0
	v_mov_b64_e32 v[116:117], 0
	v_mov_b64_e32 v[118:119], 0
	v_mov_b64_e32 v[120:121], 0
	v_mov_b64_e32 v[122:123], 0
	v_mov_b64_e32 v[124:125], 0
	v_mov_b64_e32 v[126:127], 0
	.p2align 6

.LBB0_853:
	s_ashr_i32 s19, s18, 31
	s_lshl_b64 s[20:21], s[18:19], 19
	s_add_u32 s20, s38, s20
	s_addc_u32 s21, s39, s21
	s_and_b64 s[22:23], s[2:3], exec
	s_cselect_b32 s19, s21, s31
	s_cselect_b32 s25, s20, s30
	s_ashr_i32 s17, s16, 31
	s_lshl_b64 s[22:23], s[16:17], 19
	s_add_u32 s22, s40, s22
	s_addc_u32 s23, s41, s23
	s_and_b64 s[34:35], s[2:3], exec
	s_cselect_b32 s17, s23, s29
	s_cselect_b32 s27, s22, s28
	s_add_u32 s62, s28, 0x100
	s_addc_u32 s63, s29, 0
	s_add_u32 s28, s30, 0x40080
	v_mov_b32_e32 v0, 0
	s_addc_u32 s29, s31, 0
	s_mov_b32 s64, -2
	s_waitcnt lgkmcnt(0)
	v_mov_b32_e32 v1, v0
	v_mov_b32_e32 v2, v0
	v_mov_b32_e32 v3, v0
	v_mov_b32_e32 v4, v0
	v_mov_b32_e32 v5, v0
	v_mov_b32_e32 v6, v0
	v_mov_b32_e32 v7, v0
	v_mov_b32_e32 v8, v0
	v_mov_b32_e32 v9, v0
	v_mov_b32_e32 v10, v0
	v_mov_b32_e32 v11, v0
	v_mov_b32_e32 v12, v0
	v_mov_b32_e32 v13, v0
	v_mov_b32_e32 v14, v0
	v_mov_b32_e32 v15, v0
	v_mov_b32_e32 v16, v0
	v_mov_b32_e32 v17, v0
	v_mov_b32_e32 v18, v0
	v_mov_b32_e32 v19, v0
	v_mov_b32_e32 v20, v0
	v_mov_b32_e32 v21, v0
	v_mov_b32_e32 v22, v0
	v_mov_b32_e32 v23, v0
	v_mov_b32_e32 v24, v0
	v_mov_b32_e32 v25, v0
	v_mov_b32_e32 v26, v0
	v_mov_b32_e32 v27, v0
	v_mov_b32_e32 v28, v0
	v_mov_b32_e32 v29, v0
	v_mov_b32_e32 v30, v0
	v_mov_b32_e32 v31, v0
	v_mov_b32_e32 v64, v0
	v_mov_b32_e32 v65, v0
	v_mov_b32_e32 v66, v0
	v_mov_b32_e32 v67, v0
	v_mov_b32_e32 v68, v0
	v_mov_b32_e32 v69, v0
	v_mov_b32_e32 v70, v0
	v_mov_b32_e32 v71, v0
	v_mov_b32_e32 v72, v0
	v_mov_b32_e32 v73, v0
	v_mov_b32_e32 v74, v0
	v_mov_b32_e32 v75, v0
	v_mov_b32_e32 v76, v0
	v_mov_b32_e32 v77, v0
	v_mov_b32_e32 v78, v0
	v_mov_b32_e32 v79, v0
	v_mov_b32_e32 v80, v0
	v_mov_b32_e32 v81, v0
	v_mov_b32_e32 v82, v0
	v_mov_b32_e32 v83, v0
	v_mov_b32_e32 v84, v0
	v_mov_b32_e32 v85, v0
	v_mov_b32_e32 v86, v0
	v_mov_b32_e32 v87, v0
	v_mov_b32_e32 v88, v0
	v_mov_b32_e32 v89, v0
	v_mov_b32_e32 v90, v0
	v_mov_b32_e32 v91, v0
	v_mov_b32_e32 v92, v0
	v_mov_b32_e32 v93, v0
	v_mov_b32_e32 v94, v0
	v_mov_b32_e32 v95, v0
	v_mov_b32_e32 v32, v0
	v_mov_b32_e32 v33, v0
	v_mov_b32_e32 v34, v0
	v_mov_b32_e32 v35, v0
	v_mov_b32_e32 v36, v0
	v_mov_b32_e32 v37, v0
	v_mov_b32_e32 v38, v0
	v_mov_b32_e32 v39, v0
	v_mov_b32_e32 v40, v0
	v_mov_b32_e32 v41, v0
	v_mov_b32_e32 v42, v0
	v_mov_b32_e32 v43, v0
	v_mov_b32_e32 v44, v0
	v_mov_b32_e32 v45, v0
	v_mov_b32_e32 v46, v0
	v_mov_b32_e32 v47, v0
	v_mov_b32_e32 v48, v0
	v_mov_b32_e32 v49, v0
	v_mov_b32_e32 v50, v0
	v_mov_b32_e32 v51, v0
	v_mov_b32_e32 v52, v0
	v_mov_b32_e32 v53, v0
	v_mov_b32_e32 v54, v0
	v_mov_b32_e32 v55, v0
	v_mov_b32_e32 v56, v0
	v_mov_b32_e32 v57, v0
	v_mov_b32_e32 v58, v0
	v_mov_b32_e32 v59, v0
	v_mov_b32_e32 v60, v0
	v_mov_b32_e32 v61, v0
	v_mov_b32_e32 v62, v0
	v_mov_b32_e32 v63, v0
	v_mov_b32_e32 v96, v0
	v_mov_b32_e32 v97, v0
	v_mov_b32_e32 v98, v0
	v_mov_b32_e32 v99, v0
	v_mov_b32_e32 v100, v0
	v_mov_b32_e32 v101, v0
	v_mov_b32_e32 v102, v0
	v_mov_b32_e32 v103, v0
	v_mov_b32_e32 v104, v0
	v_mov_b32_e32 v105, v0
	v_mov_b32_e32 v106, v0
	v_mov_b32_e32 v107, v0
	v_mov_b32_e32 v108, v0
	v_mov_b32_e32 v109, v0
	v_mov_b32_e32 v110, v0
	v_mov_b32_e32 v111, v0
	v_mov_b32_e32 v112, v0
	v_mov_b32_e32 v113, v0
	v_mov_b32_e32 v114, v0
	v_mov_b32_e32 v115, v0
	v_mov_b32_e32 v116, v0
	v_mov_b32_e32 v117, v0
	v_mov_b32_e32 v118, v0
	v_mov_b32_e32 v119, v0
	v_mov_b32_e32 v120, v0
	v_mov_b32_e32 v121, v0
	v_mov_b32_e32 v122, v0
	v_mov_b32_e32 v123, v0
	v_mov_b32_e32 v124, v0
	v_mov_b32_e32 v125, v0
	v_mov_b32_e32 v126, v0
	v_mov_b32_e32 v127, v0
	.p2align 6

.LBB0_929:
	s_ashr_i32 s27, s26, 31
	s_lshl_b64 s[28:29], s[26:27], 19
	s_add_u32 s28, s21, s28
	s_addc_u32 s29, s23, s29
	s_and_b64 s[30:31], s[2:3], exec
	s_cselect_b32 s27, s29, s35
	s_cselect_b32 s60, s28, s34
	s_ashr_i32 s25, s24, 31
	s_lshl_b64 s[30:31], s[24:25], 19
	s_add_u32 s30, s38, s30
	s_addc_u32 s31, s39, s31
	s_and_b64 s[36:37], s[2:3], exec
	s_cselect_b32 s25, s31, s7
	s_cselect_b32 s61, s30, s6
	s_add_u32 s62, s6, 0x100
	s_addc_u32 s63, s7, 0
	s_add_u32 s6, s34, 0x40080
	s_addc_u32 s7, s35, 0
	s_mov_b32 s64, -2
	v_mov_b64_e32 v[0:1], 0
	v_mov_b64_e32 v[2:3], 0
	v_mov_b64_e32 v[4:5], 0
	v_mov_b64_e32 v[6:7], 0
	v_mov_b64_e32 v[8:9], 0
	v_mov_b64_e32 v[10:11], 0
	v_mov_b64_e32 v[12:13], 0
	v_mov_b64_e32 v[14:15], 0
	v_mov_b64_e32 v[16:17], 0
	v_mov_b64_e32 v[18:19], 0
	v_mov_b64_e32 v[20:21], 0
	v_mov_b64_e32 v[22:23], 0
	v_mov_b64_e32 v[24:25], 0
	v_mov_b64_e32 v[26:27], 0
	v_mov_b64_e32 v[28:29], 0
	v_mov_b64_e32 v[30:31], 0
	v_mov_b64_e32 v[32:33], 0
	v_mov_b64_e32 v[34:35], 0
	v_mov_b64_e32 v[36:37], 0
	v_mov_b64_e32 v[38:39], 0
	v_mov_b64_e32 v[40:41], 0
	v_mov_b64_e32 v[42:43], 0
	v_mov_b64_e32 v[44:45], 0
	v_mov_b64_e32 v[46:47], 0
	v_mov_b64_e32 v[48:49], 0
	v_mov_b64_e32 v[50:51], 0
	v_mov_b64_e32 v[52:53], 0
	v_mov_b64_e32 v[54:55], 0
	v_mov_b64_e32 v[56:57], 0
	v_mov_b64_e32 v[58:59], 0
	v_mov_b64_e32 v[60:61], 0
	v_mov_b64_e32 v[62:63], 0
	v_mov_b64_e32 v[64:65], 0
	v_mov_b64_e32 v[66:67], 0
	v_mov_b64_e32 v[68:69], 0
	v_mov_b64_e32 v[70:71], 0
	v_mov_b64_e32 v[72:73], 0
	v_mov_b64_e32 v[74:75], 0
	v_mov_b64_e32 v[76:77], 0
	v_mov_b64_e32 v[78:79], 0
	v_mov_b64_e32 v[80:81], 0
	v_mov_b64_e32 v[82:83], 0
	v_mov_b64_e32 v[84:85], 0
	v_mov_b64_e32 v[86:87], 0
	v_mov_b64_e32 v[88:89], 0
	v_mov_b64_e32 v[90:91], 0
	v_mov_b64_e32 v[92:93], 0
	v_mov_b64_e32 v[94:95], 0
	v_mov_b64_e32 v[96:97], 0
	v_mov_b64_e32 v[98:99], 0
	v_mov_b64_e32 v[100:101], 0
	v_mov_b64_e32 v[102:103], 0
	v_mov_b64_e32 v[104:105], 0
	v_mov_b64_e32 v[106:107], 0
	v_mov_b64_e32 v[108:109], 0
	v_mov_b64_e32 v[110:111], 0
	v_mov_b64_e32 v[112:113], 0
	v_mov_b64_e32 v[114:115], 0
	v_mov_b64_e32 v[116:117], 0
	v_mov_b64_e32 v[118:119], 0
	v_mov_b64_e32 v[120:121], 0
	v_mov_b64_e32 v[122:123], 0
	v_mov_b64_e32 v[124:125], 0
	v_mov_b64_e32 v[126:127], 0
	.p2align 6

.LBB0_1001:
	s_add_u32 s48, s16, 0x100
	s_addc_u32 s49, s17, 0
	s_mov_b32 s50, -2
	v_mov_b64_e32 v[0:1], 0
	v_mov_b64_e32 v[2:3], 0
	v_mov_b64_e32 v[4:5], 0
	v_mov_b64_e32 v[6:7], 0
	v_mov_b64_e32 v[8:9], 0
	v_mov_b64_e32 v[10:11], 0
	v_mov_b64_e32 v[12:13], 0
	v_mov_b64_e32 v[14:15], 0
	v_mov_b64_e32 v[16:17], 0
	v_mov_b64_e32 v[18:19], 0
	v_mov_b64_e32 v[20:21], 0
	v_mov_b64_e32 v[22:23], 0
	v_mov_b64_e32 v[24:25], 0
	v_mov_b64_e32 v[26:27], 0
	v_mov_b64_e32 v[28:29], 0
	v_mov_b64_e32 v[30:31], 0
	v_mov_b64_e32 v[32:33], 0
	v_mov_b64_e32 v[34:35], 0
	v_mov_b64_e32 v[36:37], 0
	v_mov_b64_e32 v[38:39], 0
	v_mov_b64_e32 v[40:41], 0
	v_mov_b64_e32 v[42:43], 0
	v_mov_b64_e32 v[44:45], 0
	v_mov_b64_e32 v[46:47], 0
	v_mov_b64_e32 v[48:49], 0
	v_mov_b64_e32 v[50:51], 0
	v_mov_b64_e32 v[52:53], 0
	v_mov_b64_e32 v[54:55], 0
	v_mov_b64_e32 v[56:57], 0
	v_mov_b64_e32 v[58:59], 0
	v_mov_b64_e32 v[60:61], 0
	v_mov_b64_e32 v[62:63], 0
	v_mov_b64_e32 v[64:65], 0
	v_mov_b64_e32 v[66:67], 0
	v_mov_b64_e32 v[68:69], 0
	v_mov_b64_e32 v[70:71], 0
	v_mov_b64_e32 v[72:73], 0
	v_mov_b64_e32 v[74:75], 0
	v_mov_b64_e32 v[76:77], 0
	v_mov_b64_e32 v[78:79], 0
	v_mov_b64_e32 v[80:81], 0
	v_mov_b64_e32 v[82:83], 0
	v_mov_b64_e32 v[84:85], 0
	v_mov_b64_e32 v[86:87], 0
	v_mov_b64_e32 v[88:89], 0
	v_mov_b64_e32 v[90:91], 0
	v_mov_b64_e32 v[92:93], 0
	v_mov_b64_e32 v[94:95], 0
	v_mov_b64_e32 v[96:97], 0
	v_mov_b64_e32 v[98:99], 0
	v_mov_b64_e32 v[100:101], 0
	v_mov_b64_e32 v[102:103], 0
	v_mov_b64_e32 v[104:105], 0
	v_mov_b64_e32 v[106:107], 0
	v_mov_b64_e32 v[108:109], 0
	v_mov_b64_e32 v[110:111], 0
	v_mov_b64_e32 v[112:113], 0
	v_mov_b64_e32 v[114:115], 0
	v_mov_b64_e32 v[116:117], 0
	v_mov_b64_e32 v[118:119], 0
	v_mov_b64_e32 v[120:121], 0
	v_mov_b64_e32 v[122:123], 0
	v_mov_b64_e32 v[124:125], 0
	v_mov_b64_e32 v[126:127], 0
	.p2align 6
